# final: same code as v15 (attention tile loop rewrite), descriptor next_free_sgpr / metadata sgpr_count set to the registers actually used
# baseline (speedup 1.0000x reference)
; __global__ void __launch_bounds__(512) fwd_kernel(Args a) {
;     extern __shared__ __attribute__((aligned(16))) unsigned char lds_raw[];
	.amdhsa_kernel _Z10fwd_kernel4Args
		.amdhsa_group_segment_fixed_size 0
		.amdhsa_private_segment_fixed_size 0
		.amdhsa_kernarg_size 472
		.amdhsa_user_sgpr_count 2
		.amdhsa_user_sgpr_dispatch_ptr 0
		.amdhsa_user_sgpr_queue_ptr 0
		.amdhsa_user_sgpr_kernarg_segment_ptr 1
		.amdhsa_user_sgpr_dispatch_id 0
		.amdhsa_user_sgpr_kernarg_preload_length 0
		.amdhsa_user_sgpr_kernarg_preload_offset 0
		.amdhsa_user_sgpr_private_segment_size 0
		.amdhsa_uses_dynamic_stack 0
		.amdhsa_enable_private_segment 0
		.amdhsa_system_sgpr_workgroup_id_x 1
		.amdhsa_system_sgpr_workgroup_id_y 0
		.amdhsa_system_sgpr_workgroup_id_z 0
		.amdhsa_system_sgpr_workgroup_info 0
		.amdhsa_system_vgpr_workitem_id 2
		.amdhsa_next_free_vgpr 256
		.amdhsa_next_free_sgpr 100
		.amdhsa_accum_offset 256
		.amdhsa_reserve_vcc 1
		.amdhsa_float_round_mode_32 0
		.amdhsa_float_round_mode_16_64 0
		.amdhsa_float_denorm_mode_32 3
		.amdhsa_float_denorm_mode_16_64 3
		.amdhsa_dx10_clamp 1
		.amdhsa_ieee_mode 1
		.amdhsa_fp16_overflow 0
		.amdhsa_tg_split 0
		.amdhsa_exception_fp_ieee_invalid_op 0
		.amdhsa_exception_fp_denorm_src 0
		.amdhsa_exception_fp_ieee_div_zero 0
		.amdhsa_exception_fp_ieee_overflow 0
		.amdhsa_exception_fp_ieee_underflow 0
		.amdhsa_exception_fp_ieee_inexact 0
		.amdhsa_exception_int_div_zero 0
	.end_amdhsa_kernel

; __global__ void __launch_bounds__(512) fwd_kernel(Args a) {
;     extern __shared__ __attribute__((aligned(16))) unsigned char lds_raw[];
amdhsa.kernels:
  - .agpr_count:     0
    .args:
      - .offset:         0
        .size:           216
        .value_kind:     by_value
      - .offset:         216
        .size:           4
        .value_kind:     hidden_block_count_x
      - .offset:         220
        .size:           4
        .value_kind:     hidden_block_count_y
      - .offset:         224
        .size:           4
        .value_kind:     hidden_block_count_z
      - .offset:         228
        .size:           2
        .value_kind:     hidden_group_size_x
      - .offset:         230
        .size:           2
        .value_kind:     hidden_group_size_y
      - .offset:         232
        .size:           2
        .value_kind:     hidden_group_size_z
      - .offset:         234
        .size:           2
        .value_kind:     hidden_remainder_x
      - .offset:         236
        .size:           2
        .value_kind:     hidden_remainder_y
      - .offset:         238
        .size:           2
        .value_kind:     hidden_remainder_z
      - .offset:         256
        .size:           8
        .value_kind:     hidden_global_offset_x
      - .offset:         264
        .size:           8
        .value_kind:     hidden_global_offset_y
      - .offset:         272
        .size:           8
        .value_kind:     hidden_global_offset_z
      - .offset:         280
        .size:           2
        .value_kind:     hidden_grid_dims
      - .offset:         304
        .size:           8
        .value_kind:     hidden_multigrid_sync_arg
      - .offset:         336
        .size:           4
        .value_kind:     hidden_dynamic_lds_size
    .group_segment_fixed_size: 0
    .kernarg_segment_align: 8
    .kernarg_segment_size: 472
    .language:       OpenCL C
    .language_version:
      - 2
      - 0
    .max_flat_workgroup_size: 512
    .name:           _Z10fwd_kernel4Args
    .private_segment_fixed_size: 0
    .sgpr_count:     106
    .sgpr_spill_count: 69
    .symbol:         _Z10fwd_kernel4Args.kd
    .uniform_work_group_size: 1
    .uses_dynamic_stack: false
    .vgpr_count:     256
    .vgpr_spill_count: 0
    .wavefront_size: 64
